# P1: waves 2-4 convert 16 items each first, then sample tasks, then left-over conversion; waves 5-7 original order (on top of the 0x6000 split)
# baseline (speedup 1.0000x reference)
.LBB0_77:
	s_mov_b32 s101, 0
	s_cmp_gt_i32 s96, 1
	s_cselect_b64 s[0:1], -1, 0
	s_cmp_lt_i32 s97, 2
	s_cselect_b64 s[2:3], -1, 0
	s_or_b64 s[0:1], s[0:1], s[2:3]
	s_and_b64 vcc, exec, s[0:1]
	s_cbranch_vccnz .LBB0_170
	s_cmpk_gt_u32 s63, 0x7f
	s_mov_b64 s[0:1], -1
	s_cbranch_scc0 .LBB0_83
	s_cmp_lt_u32 s93, 5
	s_cbranch_scc0 .Lp1_sample
	s_mov_b32 s101, 1
	s_movk_i32 s100, 17
	v_writelane_b32 v253, s12, 0
	v_writelane_b32 v253, s13, 1
	v_writelane_b32 v253, s14, 2
	v_writelane_b32 v253, s15, 3
	v_writelane_b32 v253, s48, 4
	v_writelane_b32 v253, s49, 5
	s_branch .LBB0_89
.Lp1_resume:
	s_mov_b32 s101, 2
	v_readlane_b32 s12, v253, 0
	v_readlane_b32 s13, v253, 1
	v_readlane_b32 s14, v253, 2
	v_readlane_b32 s15, v253, 3
	v_readlane_b32 s48, v253, 4
	v_readlane_b32 s49, v253, 5
	s_waitcnt vmcnt(0) lgkmcnt(0)
.Lp1_sample:
	s_mul_i32 s0, s94, 6
	s_add_i32 s0, s93, s0
	s_add_i32 s30, s0, -2
	s_cmpk_gt_i32 s30, 0x1fff
	s_cbranch_scc1 .LBB0_82
	s_add_u32 s0, s84, 0x48c00000
	s_addc_u32 s1, s85, 0
	s_add_u32 s2, s84, 0x48c20000
	s_addc_u32 s3, s85, 0
	s_add_u32 s4, s84, 0x48d20000
	s_addc_u32 s5, s85, 0
	v_lshrrev_b32_e32 v1, 2, v0
	s_add_u32 s6, s84, 0x48c10000
	v_and_b32_e32 v2, 12, v1
	v_and_b32_e32 v1, 3, v0
	v_lshrrev_b32_e32 v4, 1, v154
	s_mul_i32 s22, s93, 0x2200
	s_addc_u32 s7, s85, 0
	v_and_or_b32 v5, v4, 4, v1
	s_add_i32 s22, s22, 0
	v_lshrrev_b32_e32 v3, 5, v154
	v_or_b32_e32 v87, 0x2000, v5
	v_or_b32_e32 v89, 0x2008, v5
	s_movk_i32 s24, 0x440
	v_mov_b32_e32 v5, s22
	v_mad_u32_u24 v9, v3, s24, v5
	s_add_u32 s24, s90, 0x9170000
	s_addc_u32 s25, s91, 0
	v_and_b32_e32 v68, 31, v0
	v_mov_b32_e32 v71, 0
	v_lshlrev_b32_e32 v70, 2, v2
	v_and_b32_e32 v1, 2, v4
	v_lshrrev_b32_e32 v4, 4, v0
	s_add_u32 s26, s90, 0x9970000
	s_waitcnt lgkmcnt(0)
	v_lshl_add_u64 v[72:73], s[48:49], 0, v[70:71]
	v_lshl_add_u64 v[74:75], s[18:19], 0, v[70:71]
	v_lshlrev_b32_e32 v8, 2, v68
	v_and_or_b32 v69, v4, 1, v1
	v_lshlrev_b32_e32 v91, 1, v3
	s_addc_u32 s27, s91, 0
	v_lshlrev_b32_e32 v4, 3, v3
	v_and_b32_e32 v3, 15, v0
	s_movk_i32 s22, 0x110
	v_lshlrev_b32_e32 v70, 1, v2
	s_add_u32 s28, s84, 0x49100000
	v_mad_u32_u24 v3, v3, s22, v5
	v_and_b32_e32 v5, 48, v0
	v_lshl_add_u64 v[6:7], s[84:85], 0, v[70:71]
	s_mov_b64 s[34:35], 0x33800000
	v_add_u32_e32 v101, v9, v8
	s_movk_i32 s31, 0x2000
	s_mov_b32 s23, 0
	s_addc_u32 s29, s85, 0
	v_lshl_add_u64 v[76:77], v[6:7], 0, s[34:35]
	s_mul_i32 s33, s92, 6
	v_lshlrev_b32_e32 v93, 4, v154
	v_mov_b32_e32 v97, s11
	v_mov_b32_e32 v98, s9
	v_mov_b32_e32 v99, s10
	v_mov_b32_e32 v100, s8
	v_lshlrev_b32_e32 v70, 2, v4
	v_lshlrev_b32_e32 v78, 2, v2
	v_mov_b32_e32 v79, v71
	v_add_u32_e32 v102, v3, v5
	v_add_u32_e32 v103, 0x800, v101
	v_add_u32_e32 v104, 0xa00, v101
	v_add_u32_e32 v105, 0x1000, v101
	v_add_u32_e32 v106, 0x1400, v101
	v_add_u32_e32 v107, 0x1800, v101
	v_add_u32_e32 v108, 0x1a00, v101
	v_add_u32_e32 v109, 0x1c00, v101

.LBB0_92:
	s_cmp_eq_u32 s101, 1
	s_cbranch_scc0 .Lcv_go
	s_sub_u32 s100, s100, 1
	s_cmp_eq_u32 s100, 0
	s_cbranch_scc1 .LBB0_120

.LBB0_120:
	s_cmp_eq_u32 s101, 1
	s_cbranch_scc1 .Lp1_resume
	s_cmp_eq_u32 s101, 3
	s_cbranch_scc1 .Lp2_conv_ret
	s_cmp_lt_i32 s97, 3
	s_cbranch_scc1 .LBB0_170
	s_waitcnt vmcnt(0)
	v_cmp_eq_u32_e32 vcc, 0, v0
	s_barrier
	s_and_saveexec_b64 s[0:1], vcc
	s_cbranch_execz .LBB0_169
	v_readlane_b32 s2, v240, 12
	s_waitcnt vmcnt(0) expcnt(0) lgkmcnt(0)
	s_nop 0
	v_mov_b32_e32 v1, s2
	ds_read_b32 v3, v1
	ds_read_b32 v1, v1 offset:4
	s_waitcnt lgkmcnt(1)
	v_cmp_ne_u32_e32 vcc, 0, v3
	s_cbranch_vccnz .LBB0_137
	v_readlane_b32 s2, v240, 0
	v_readlane_b32 s3, v240, 1
	s_load_dwordx2 s[6:7], s[2:3], 0x4
	s_add_u32 s2, s84, 0x4200
	s_addc_u32 s3, s85, 0
	s_add_u32 s4, s84, 0x4400
	s_addc_u32 s5, s85, 0
	s_waitcnt lgkmcnt(0)
	s_mul_i32 s33, s6, s92
	s_add_u32 s6, s84, 0x4500
	s_mul_i32 s33, s33, s7
	s_addc_u32 s7, s85, 0
	s_add_u32 s12, s84, 0x4600
	s_addc_u32 s13, s85, 0
	s_add_u32 s14, s84, 0x4700
	s_addc_u32 s15, s85, 0
	s_add_u32 s22, s84, 0x4800
	s_addc_u32 s23, s85, 0
	s_add_u32 s24, s84, 0x4900
	s_addc_u32 s25, s85, 0
	s_add_u32 s26, s84, 0x4a00
	s_addc_u32 s27, s85, 0
	s_add_u32 s28, s84, 0x4b00
	s_addc_u32 s29, s85, 0
	s_add_u32 s30, s84, 0x4c00
	s_addc_u32 s31, s85, 0
	s_add_u32 s34, s84, 0x4d00
	s_addc_u32 s35, s85, 0
	s_add_u32 s36, s84, 0x4e00
	s_addc_u32 s37, s85, 0
	s_add_u32 s38, s84, 0x4f00
	s_addc_u32 s39, s85, 0
	s_add_u32 s40, s84, 0x5000
	s_addc_u32 s41, s85, 0
	s_add_u32 s42, s84, 0x5100
	s_addc_u32 s43, s85, 0
	s_add_u32 s44, s84, 0x5200
	s_addc_u32 s45, s85, 0
	s_add_u32 s46, s84, 0x5300
	s_addc_u32 s47, s85, 0
	s_mov_b32 s56, 1
	v_mov_b32_e32 v17, 0
	s_branch .LBB0_125
